# norm_rows (memory-token RMSNorm): row and gain chunks loaded up front instead of ~12 dependent load/wait round trips per row
# speedup vs baseline: 1.0026x; 1.0026x over previous
; __device__ __forceinline__ unsigned cvt_pk_bf16(float lo, float hi) { f32x2 v = {lo, hi}; bf16x2_t b = __builtin_convertvector(v, bf16x2_t); return __builtin_bit_cast(unsigned, b); }
; __device__ __forceinline__ float wave_sum(float v) {
; #pragma unroll
;     for (int o = 1; o < 64; o <<= 1) v += __shfl_xor(v, o);
;     return v;
; }
; __device__ __forceinline__ void norm_rows(const float* X, const float* gvec, bf16_t* out, float* fout, int nrows, int gw, int ngw, int lane) {
;     for (int row = gw; row < nrows; row += ngw) {
;         const f32x4* xr = (const f32x4*)(X + (size_t)row * DM) + lane;
;         f32x4 v[8]; float ss = 0.f;
; #pragma unroll
;         for (int j = 0; j < 8; ++j) { v[j] = xr[64 * j]; ss += (v[j][0] * v[j][0] + v[j][1] * v[j][1]) + (v[j][2] * v[j][2] + v[j][3] * v[j][3]); }
;         ss = wave_sum(ss);
;         const float r = rsqrtf(ss * (1.f / DM) + EPS);
; #pragma unroll
;         for (int j = 0; j < 8; ++j) { const f32x4 gv = ((const f32x4*)gvec)[lane + 64 * j]; const f32x4 y = v[j] * r * gv;
;             if (fout) { ((f32x4*)(fout + (size_t)row * DM))[lane + 64 * j] = y; }
;             else { u32x2 w; w.x = cvt_pk_bf16(y[0], y[1]); w.y = cvt_pk_bf16(y[2], y[3]); ((u32x2*)(out + (size_t)row * DM))[lane + 64 * j] = w; } }
;     }
; }
.LBB0_1460:
	global_load_dwordx4 v[2:5], v[60:61], off offset:-4096
	global_load_dwordx4 v[6:9], v[60:61], off offset:-3072
	global_load_dwordx4 v[10:13], v[60:61], off offset:-2048
	global_load_dwordx4 v[14:17], v[60:61], off offset:-1024
	global_load_dwordx4 v[18:21], v[60:61], off
	global_load_dwordx4 v[22:25], v[60:61], off offset:1024
	global_load_dwordx4 v[26:29], v[60:61], off offset:2048
	global_load_dwordx4 v[30:33], v[60:61], off offset:3072
	global_load_dwordx4 v[84:87], v[50:51], off
	global_load_dwordx4 v[88:91], v[50:51], off offset:1024
	global_load_dwordx4 v[92:95], v[50:51], off offset:2048
	global_load_dwordx4 v[96:99], v[50:51], off offset:3072
	global_load_dwordx4 v[100:103], v[52:53], off
	global_load_dwordx4 v[104:107], v[54:55], off
	global_load_dwordx4 v[108:111], v[56:57], off
	global_load_dwordx4 v[112:115], v[58:59], off
	v_lshl_add_u64 v[116:117], v[62:63], 0, v[36:37]
	v_lshl_add_u64 v[118:119], v[62:63], 0, v[40:41]
	s_waitcnt vmcnt(15)
	v_mul_f32_e32 v43, v3, v3
	v_mul_f32_e32 v45, v5, v5
	v_fmac_f32_e32 v43, v2, v2
	v_fmac_f32_e32 v45, v4, v4
	v_add_f32_e32 v43, v43, v45
	s_waitcnt vmcnt(14)
	v_mul_f32_e32 v78, v7, v7
	v_mul_f32_e32 v79, v9, v9
	v_fmac_f32_e32 v78, v6, v6
	v_fmac_f32_e32 v79, v8, v8
	v_add_f32_e32 v78, v78, v79
	v_add_f32_e32 v43, v43, v78
	s_waitcnt vmcnt(13)
	v_mul_f32_e32 v78, v11, v11
	v_mul_f32_e32 v79, v13, v13
	v_fmac_f32_e32 v78, v10, v10
	v_fmac_f32_e32 v79, v12, v12
	v_add_f32_e32 v78, v78, v79
	v_add_f32_e32 v43, v43, v78
	s_waitcnt vmcnt(12)
	v_mul_f32_e32 v78, v15, v15
	v_mul_f32_e32 v79, v17, v17
	v_fmac_f32_e32 v78, v14, v14
	v_fmac_f32_e32 v79, v16, v16
	v_add_f32_e32 v78, v78, v79
	v_add_f32_e32 v43, v43, v78
	s_waitcnt vmcnt(11)
	v_mul_f32_e32 v78, v19, v19
	v_mul_f32_e32 v79, v21, v21
	v_fmac_f32_e32 v78, v18, v18
	v_fmac_f32_e32 v79, v20, v20
	v_add_f32_e32 v78, v78, v79
	v_add_f32_e32 v43, v43, v78
	s_waitcnt vmcnt(10)
	v_mul_f32_e32 v78, v23, v23
	v_mul_f32_e32 v79, v25, v25
	v_fmac_f32_e32 v78, v22, v22
	v_fmac_f32_e32 v79, v24, v24
	v_add_f32_e32 v78, v78, v79
	v_add_f32_e32 v43, v43, v78
	s_waitcnt vmcnt(9)
	v_mul_f32_e32 v78, v27, v27
	v_mul_f32_e32 v79, v29, v29
	v_fmac_f32_e32 v78, v26, v26
	v_fmac_f32_e32 v79, v28, v28
	v_add_f32_e32 v78, v78, v79
	v_add_f32_e32 v43, v43, v78
	s_waitcnt vmcnt(8)
	v_mul_f32_e32 v78, v31, v31
	v_mul_f32_e32 v79, v33, v33
	v_fmac_f32_e32 v78, v30, v30
	v_fmac_f32_e32 v79, v32, v32
	v_add_f32_e32 v78, v78, v79
	v_add_f32_e32 v43, v43, v78
	ds_bpermute_b32 v45, v71, v43
	s_waitcnt lgkmcnt(0)
	v_add_f32_e32 v43, v43, v45
	ds_bpermute_b32 v45, v72, v43
	s_waitcnt lgkmcnt(0)
	v_add_f32_e32 v43, v43, v45
	ds_bpermute_b32 v45, v73, v43
	s_waitcnt lgkmcnt(0)
	v_add_f32_e32 v43, v43, v45
	ds_bpermute_b32 v45, v74, v43
	s_waitcnt lgkmcnt(0)
	v_add_f32_e32 v43, v43, v45
	ds_bpermute_b32 v45, v75, v43
	s_waitcnt lgkmcnt(0)
	v_add_f32_e32 v43, v43, v45
	ds_bpermute_b32 v45, v76, v43
	s_waitcnt lgkmcnt(0)
	v_add_f32_e32 v43, v43, v45
	v_fmamk_f32 v43, v43, 0x3a000000, v203
	v_cmp_gt_f32_e32 vcc, s80, v43
	v_mul_f32_e32 v45, 0x4b800000, v43
	s_nop 0
	v_cndmask_b32_e32 v43, v43, v45, vcc
	v_rsq_f32_e32 v43, v43
	s_nop 0
	v_mul_f32_e32 v45, 0x45800000, v43
	v_cndmask_b32_e32 v64, v43, v45, vcc
	s_waitcnt vmcnt(7)
	v_pk_mul_f32 v[2:3], v[2:3], v[64:65] op_sel_hi:[1,0]
	v_pk_mul_f32 v[4:5], v[4:5], v[64:65] op_sel_hi:[1,0]
	v_pk_mul_f32 v[2:3], v[2:3], v[84:85]
	v_pk_mul_f32 v[4:5], v[4:5], v[86:87]
	v_cvt_pk_bf16_f32 v2, v2, v3
	v_cvt_pk_bf16_f32 v3, v4, v5
	global_store_dwordx2 v[116:117], v[2:3], off
	s_waitcnt vmcnt(7)
	v_pk_mul_f32 v[6:7], v[6:7], v[64:65] op_sel_hi:[1,0]
	v_pk_mul_f32 v[8:9], v[8:9], v[64:65] op_sel_hi:[1,0]
	v_pk_mul_f32 v[6:7], v[6:7], v[88:89]
	v_pk_mul_f32 v[8:9], v[8:9], v[90:91]
	v_cvt_pk_bf16_f32 v6, v6, v7
	v_cvt_pk_bf16_f32 v7, v8, v9
	global_store_dwordx2 v[118:119], v[6:7], off offset:-1536
	s_waitcnt vmcnt(7)
	v_pk_mul_f32 v[10:11], v[10:11], v[64:65] op_sel_hi:[1,0]
	v_pk_mul_f32 v[12:13], v[12:13], v[64:65] op_sel_hi:[1,0]
	v_pk_mul_f32 v[10:11], v[10:11], v[92:93]
	v_pk_mul_f32 v[12:13], v[12:13], v[94:95]
	v_cvt_pk_bf16_f32 v10, v10, v11
	v_cvt_pk_bf16_f32 v11, v12, v13
	global_store_dwordx2 v[118:119], v[10:11], off offset:-1024
	s_waitcnt vmcnt(7)
	v_pk_mul_f32 v[14:15], v[14:15], v[64:65] op_sel_hi:[1,0]
	v_pk_mul_f32 v[16:17], v[16:17], v[64:65] op_sel_hi:[1,0]
	v_pk_mul_f32 v[14:15], v[14:15], v[96:97]
	v_pk_mul_f32 v[16:17], v[16:17], v[98:99]
	v_cvt_pk_bf16_f32 v14, v14, v15
	v_cvt_pk_bf16_f32 v15, v16, v17
	global_store_dwordx2 v[118:119], v[14:15], off offset:-512
	s_waitcnt vmcnt(7)
	v_pk_mul_f32 v[18:19], v[18:19], v[64:65] op_sel_hi:[1,0]
	v_pk_mul_f32 v[20:21], v[20:21], v[64:65] op_sel_hi:[1,0]
	v_pk_mul_f32 v[18:19], v[18:19], v[100:101]
	v_pk_mul_f32 v[20:21], v[20:21], v[102:103]
	v_cvt_pk_bf16_f32 v18, v18, v19
	v_cvt_pk_bf16_f32 v19, v20, v21
	global_store_dwordx2 v[118:119], v[18:19], off
	s_waitcnt vmcnt(7)
	v_pk_mul_f32 v[22:23], v[22:23], v[64:65] op_sel_hi:[1,0]
	v_pk_mul_f32 v[24:25], v[24:25], v[64:65] op_sel_hi:[1,0]
	v_pk_mul_f32 v[22:23], v[22:23], v[104:105]
	v_pk_mul_f32 v[24:25], v[24:25], v[106:107]
	v_cvt_pk_bf16_f32 v22, v22, v23
	v_cvt_pk_bf16_f32 v23, v24, v25
	global_store_dwordx2 v[118:119], v[22:23], off offset:512
	s_waitcnt vmcnt(7)
	v_pk_mul_f32 v[26:27], v[26:27], v[64:65] op_sel_hi:[1,0]
	v_pk_mul_f32 v[28:29], v[28:29], v[64:65] op_sel_hi:[1,0]
	v_pk_mul_f32 v[26:27], v[26:27], v[108:109]
	v_pk_mul_f32 v[28:29], v[28:29], v[110:111]
	v_cvt_pk_bf16_f32 v26, v26, v27
	v_cvt_pk_bf16_f32 v27, v28, v29
	global_store_dwordx2 v[118:119], v[26:27], off offset:1024
	s_waitcnt vmcnt(7)
	v_pk_mul_f32 v[30:31], v[30:31], v[64:65] op_sel_hi:[1,0]
	v_pk_mul_f32 v[32:33], v[32:33], v[64:65] op_sel_hi:[1,0]
	v_pk_mul_f32 v[30:31], v[30:31], v[112:113]
	v_pk_mul_f32 v[32:33], v[32:33], v[114:115]
	v_cvt_pk_bf16_f32 v30, v30, v31
	v_cvt_pk_bf16_f32 v31, v32, v33
	global_store_dwordx2 v[118:119], v[30:31], off offset:1536
	v_lshl_add_u64 v[60:61], v[60:61], 0, s[26:27]
	v_lshl_add_u64 v[62:63], v[62:63], 0, s[76:77]
	s_add_i32 s0, s0, s70
	s_cmpk_lt_i32 s0, 0x400
	s_cbranch_scc1 .LBB0_1460
	s_branch .LBB0_1457
